# stack variant with the barrier-shadow attention units taken from the first 256 units instead of the last 256
# baseline (speedup 1.0000x reference)
.Lb2_first:
	s_mov_b32 s14, 2
	v_readlane_b32 s42, v252, 0
	v_writelane_b32 v255, s14, 41
	s_addk_i32 s42, 0x2c8
	s_branch .Lq_aunit

.LBB0_329:
	s_or_b64 exec, exec, s[10:11]
	s_lshl_b32 s14, s32, 1
	s_and_b32 s14, s14, 4
	s_add_i32 s14, s14, 0x20040
	v_mov_b32_e32 v2, s14
	s_and_b32 s32, s32, 2
	s_xor_b32 s32, s32, 2
	s_waitcnt lgkmcnt(0)
	s_barrier
	ds_read_b32 v0, v2
	s_mov_b64 s[10:11], -1
	s_waitcnt lgkmcnt(0)
	v_readfirstlane_b32 s42, v0
	s_movk_i32 s14, 0x747
	s_cmp_eq_u32 s3, 0x100
	s_cselect_b32 s14, 0x647, s14
	s_cmp_gt_i32 s42, s14
	s_cbranch_scc1 .LBB0_324
	s_cmp_eq_u32 s3, 0x100
	s_cselect_b32 s14, 0x100, 0
	s_cmpk_gt_u32 s42, 0x2c7
	s_cselect_b32 s14, s14, 0
	s_add_u32 s42, s42, s14
	s_cmpk_gt_i32 s42, 0x47
	s_cbranch_scc0 .LBB0_405
	s_cmpk_gt_u32 s42, 0x2c7
	s_cbranch_scc0 .LBB0_346
